# bias1: loop-invariant shift-vector loads hoisted and all three weight rows prefetched before the loop (one round trip instead of three), on top of the P4 prefetch
# baseline (speedup 1.0000x reference)
; __device__ __forceinline__ float bflo(unsigned w) { return __uint_as_float(w << 16); }
; __device__ __forceinline__ float bfhi(unsigned w) { return __uint_as_float(w & 0xffff0000u); }
; __device__ __forceinline__ void bias1_phase(const bf16* W1t, const float* mod1, float* biasp, int G) {
;     int tid = threadIdx.x; asm volatile("" : "+v"(tid)); const int lane = tid & 63, wave = tid >> 6;
;     for (int p = blockIdx.x * NWAVES + wave; p < 4112; p += G * NWAVES) {
;         float s0 = 0.f, s1 = 0.f;
; #pragma unroll
;         for (int j = 0; j < 2; ++j) { const int k0 = 8 * lane + 512 * j; const v4u w = *(const v4u*)(W1t + (size_t)p * D + k0);
; #pragma unroll
;             for (int e = 0; e < 4; ++e) { const float wl = bflo(w[e]), wh = bfhi(w[e]);
;                 s0 += wl * mod1[k0 + 2 * e] + wh * mod1[k0 + 2 * e + 1]; s1 += wl * mod1[3072 + k0 + 2 * e] + wh * mod1[3072 + k0 + 2 * e + 1]; } }
.LBB0_470:
	v_mov_b32_e32 v1, v216
	v_readlane_b32 s0, v249, 3
	v_ashrrev_i32_e32 v0, 6, v1
	s_nop 0
	v_add_u32_e32 v0, s0, v0
	s_movk_i32 s0, 0x1010
	v_cmp_gt_i32_e32 vcc, s0, v0
	s_and_saveexec_b64 s[0:1], vcc
	v_readlane_b32 s24, v249, 5
	v_readlane_b32 s25, v249, 6
	s_cbranch_execz .LBB0_475
	v_cmp_lt_i32_e32 vcc, v215, v209
	v_and_b32_e32 v20, 63, v1
	s_add_u32 s14, s10, 0x26000
	v_cndmask_b32_e32 v1, v208, v215, vcc
	v_cmp_lt_i32_e32 vcc, v214, v209
	v_lshlrev_b32_e32 v14, 2, v1
	s_addc_u32 s15, s11, 0
	v_cndmask_b32_e32 v1, v208, v214, vcc
	v_cmp_lt_i32_e32 vcc, v213, v209
	v_lshlrev_b32_e32 v15, 2, v1
	v_lshlrev_b32_e32 v6, 5, v20
	v_cndmask_b32_e32 v1, v208, v213, vcc
	v_cmp_lt_i32_e32 vcc, v212, v209
	v_lshlrev_b32_e32 v16, 2, v1
	v_mov_b32_e32 v7, 0
	v_cndmask_b32_e32 v1, v208, v212, vcc
	v_cmp_lt_i32_e32 vcc, v211, v209
	v_lshlrev_b32_e32 v17, 2, v1
	v_lshl_add_u64 v[2:3], s[14:15], 0, v[6:7]
	v_cndmask_b32_e32 v1, v208, v211, vcc
	v_cmp_lt_i32_e32 vcc, v210, v209
	v_lshlrev_b32_e32 v18, 2, v1
	v_or_b32_e32 v6, 0x800, v6
	v_cndmask_b32_e32 v1, v208, v210, vcc
	v_lshlrev_b32_e32 v19, 2, v1
	v_ashrrev_i32_e32 v1, 31, v0
	v_lshlrev_b64 v[12:13], 11, v[0:1]
	v_lshl_add_u64 v[6:7], s[14:15], 0, v[6:7]
	v_lshl_add_u64 v[10:11], v[0:1], 2, s[10:11]
	s_mov_b64 s[14:15], 0x140000
	v_lshl_or_b32 v12, v20, 4, v12
	s_mov_b64 s[16:17], 0x3000
	v_lshl_add_u64 v[10:11], v[10:11], 0, s[14:15]
	s_ashr_i32 s5, s4, 31
	v_lshl_add_u64 v[12:13], s[10:11], 0, v[12:13]
	s_mov_b64 s[14:15], 0xa00000
	v_cmp_eq_u32_e64 s[38:39], 0, v20
	v_lshl_add_u64 v[4:5], v[2:3], 0, s[16:17]
	v_lshl_add_u64 v[8:9], v[6:7], 0, s[16:17]
	s_lshl_b64 s[40:41], s[4:5], 2
	v_lshl_add_u64 v[12:13], v[12:13], 0, s[14:15]
	s_lshl_b64 s[42:43], s[4:5], 11
	s_mov_b64 s[44:45], 0
	s_mov_b32 s32, 0
	global_load_dwordx4 v[130:133], v[2:3], off
	global_load_dwordx4 v[134:137], v[4:5], off
	global_load_dwordx4 v[138:141], v[2:3], off offset:16
	global_load_dwordx4 v[142:145], v[4:5], off offset:16
	global_load_dwordx4 v[146:149], v[6:7], off
	global_load_dwordx4 v[150:153], v[8:9], off
	global_load_dwordx4 v[154:157], v[6:7], off offset:16
	global_load_dwordx4 v[158:161], v[8:9], off offset:16
	global_load_dwordx4 v[20:23], v[12:13], off
	global_load_dwordx4 v[24:27], v[12:13], off offset:1024
	v_lshl_add_u64 v[78:79], v[12:13], 0, s[42:43]
	global_load_dwordx4 v[110:113], v[78:79], off
	global_load_dwordx4 v[114:117], v[78:79], off offset:1024
	v_lshl_add_u64 v[78:79], v[78:79], 0, s[42:43]
	global_load_dwordx4 v[118:121], v[78:79], off
	global_load_dwordx4 v[122:125], v[78:79], off offset:1024
	s_branch .LBB0_473

; __device__ __forceinline__ float bflo(unsigned w) { return __uint_as_float(w << 16); }
; __device__ __forceinline__ float bfhi(unsigned w) { return __uint_as_float(w & 0xffff0000u); }
; __device__ __forceinline__ void bias1_phase(const bf16* W1t, const float* mod1, float* biasp, int G) {
;     ...
;     for (int p = blockIdx.x * NWAVES + wave; p < 4112; p += G * NWAVES) {
;         float s0 = 0.f, s1 = 0.f;
; #pragma unroll
;         for (int j = 0; j < 2; ++j) { const int k0 = 8 * lane + 512 * j; const v4u w = *(const v4u*)(W1t + (size_t)p * D + k0);
; #pragma unroll
;             for (int e = 0; e < 4; ++e) { const float wl = bflo(w[e]), wh = bfhi(w[e]);
;                 s0 += wl * mod1[k0 + 2 * e] + wh * mod1[k0 + 2 * e + 1]; s1 += wl * mod1[3072 + k0 + 2 * e] + wh * mod1[3072 + k0 + 2 * e + 1]; } }
;         s0 = wave_sum(s0); s1 = wave_sum(s1);
;         if (lane == 0) { biasp[p] = s0; biasp[4352 + p] = s1; }
;     }
.LBB0_473:
	s_waitcnt lgkmcnt(0)
	s_cmp_eq_u32 s32, 1
	s_cbranch_scc1 .Lb1_r1
	s_cmp_eq_u32 s32, 2
	s_cbranch_scc1 .Lb1_r2
	s_waitcnt vmcnt(4)
	s_branch .Lb1_go
.Lb1_r1:
	s_waitcnt vmcnt(4)
	v_mov_b64_e32 v[20:21], v[110:111]
	v_mov_b64_e32 v[22:23], v[112:113]
	v_mov_b64_e32 v[24:25], v[114:115]
	v_mov_b64_e32 v[26:27], v[116:117]
	s_branch .Lb1_go
.Lb1_r2:
	s_waitcnt vmcnt(4)
	v_mov_b64_e32 v[20:21], v[118:119]
	v_mov_b64_e32 v[22:23], v[120:121]
	v_mov_b64_e32 v[24:25], v[122:123]
	v_mov_b64_e32 v[26:27], v[124:125]
.Lb1_go:
	s_add_i32 s32, s32, 1
	v_mov_b64_e32 v[28:29], v[130:131]
	v_mov_b64_e32 v[30:31], v[132:133]
	v_mov_b64_e32 v[32:33], v[134:135]
	v_mov_b64_e32 v[34:35], v[136:137]
	v_mov_b64_e32 v[36:37], v[138:139]
	v_mov_b64_e32 v[38:39], v[140:141]
	v_mov_b64_e32 v[40:41], v[142:143]
	v_mov_b64_e32 v[42:43], v[144:145]
	v_mov_b64_e32 v[44:45], v[146:147]
	v_mov_b64_e32 v[46:47], v[148:149]
	v_mov_b64_e32 v[48:49], v[150:151]
	v_mov_b64_e32 v[50:51], v[152:153]
	v_mov_b64_e32 v[52:53], v[154:155]
	v_mov_b64_e32 v[54:55], v[156:157]
	v_mov_b64_e32 v[56:57], v[158:159]
	v_mov_b64_e32 v[58:59], v[160:161]
	v_lshlrev_b32_e32 v1, 16, v20
	v_and_b32_e32 v20, 0xffff0000, v20
	v_lshlrev_b32_e32 v60, 16, v21
	v_and_b32_e32 v21, 0xffff0000, v21
	v_mul_f32_e32 v29, v29, v20
	v_mul_f32_e32 v20, v33, v20
	v_lshlrev_b32_e32 v61, 16, v22
	v_and_b32_e32 v22, 0xffff0000, v22
	v_mul_f32_e32 v31, v31, v21
	v_mul_f32_e32 v21, v35, v21
	v_fmac_f32_e32 v29, v28, v1
	v_fmac_f32_e32 v20, v32, v1
	v_lshlrev_b32_e32 v62, 16, v23
	v_and_b32_e32 v23, 0xffff0000, v23
	v_mul_f32_e32 v33, v37, v22
	v_mul_f32_e32 v22, v41, v22
	v_fmac_f32_e32 v31, v30, v60
	v_fmac_f32_e32 v21, v34, v60
	v_add_f32_e32 v1, 0, v29
	v_add_f32_e32 v20, 0, v20
	v_lshlrev_b32_e32 v63, 16, v24
	v_and_b32_e32 v24, 0xffff0000, v24
	v_mul_f32_e32 v35, v39, v23
	v_mul_f32_e32 v23, v43, v23
	v_fmac_f32_e32 v33, v36, v61
	v_fmac_f32_e32 v22, v40, v61
	v_add_f32_e32 v1, v1, v31
	v_add_f32_e32 v20, v20, v21
	v_lshlrev_b32_e32 v64, 16, v25
	v_and_b32_e32 v25, 0xffff0000, v25
	v_mul_f32_e32 v37, v45, v24
	v_mul_f32_e32 v24, v49, v24
	v_fmac_f32_e32 v35, v38, v62
	v_fmac_f32_e32 v23, v42, v62
	v_add_f32_e32 v1, v1, v33
	v_add_f32_e32 v20, v20, v22
	v_lshlrev_b32_e32 v65, 16, v26
	v_and_b32_e32 v26, 0xffff0000, v26
	v_mul_f32_e32 v39, v47, v25
	v_mul_f32_e32 v25, v51, v25
	v_fmac_f32_e32 v37, v44, v63
	v_fmac_f32_e32 v24, v48, v63
	v_add_f32_e32 v1, v1, v35
	v_add_f32_e32 v20, v20, v23
	v_lshlrev_b32_e32 v66, 16, v27
	v_and_b32_e32 v27, 0xffff0000, v27
	v_mul_f32_e32 v41, v53, v26
	v_mul_f32_e32 v26, v57, v26
	v_fmac_f32_e32 v39, v46, v64
	v_fmac_f32_e32 v25, v50, v64
	v_add_f32_e32 v1, v1, v37
	v_add_f32_e32 v20, v20, v24
	v_mul_f32_e32 v43, v55, v27
	v_mul_f32_e32 v27, v59, v27
	v_fmac_f32_e32 v41, v52, v65
	v_fmac_f32_e32 v26, v56, v65
	v_add_f32_e32 v1, v1, v39
	v_add_f32_e32 v20, v20, v25
	v_fmac_f32_e32 v43, v54, v66
	v_fmac_f32_e32 v27, v58, v66
	v_add_f32_e32 v1, v1, v41
	v_add_f32_e32 v20, v20, v26
	v_add_f32_e32 v1, v1, v43
	v_add_f32_e32 v20, v20, v27
	ds_bpermute_b32 v21, v14, v1
	ds_bpermute_b32 v22, v14, v20
	s_waitcnt lgkmcnt(1)
	v_add_f32_e32 v1, v1, v21
	s_waitcnt lgkmcnt(0)
	v_add_f32_e32 v20, v20, v22
	ds_bpermute_b32 v21, v15, v1
	ds_bpermute_b32 v22, v15, v20
	s_waitcnt lgkmcnt(1)
	v_add_f32_e32 v1, v1, v21
	s_waitcnt lgkmcnt(0)
	v_add_f32_e32 v20, v20, v22
	ds_bpermute_b32 v21, v16, v1
	ds_bpermute_b32 v22, v16, v20
	s_waitcnt lgkmcnt(1)
	v_add_f32_e32 v1, v1, v21
	s_waitcnt lgkmcnt(0)
	v_add_f32_e32 v20, v20, v22
	ds_bpermute_b32 v21, v17, v1
	ds_bpermute_b32 v22, v17, v20
	s_waitcnt lgkmcnt(1)
	v_add_f32_e32 v1, v1, v21
	s_waitcnt lgkmcnt(0)
	v_add_f32_e32 v20, v20, v22
	ds_bpermute_b32 v21, v18, v1
	ds_bpermute_b32 v22, v18, v20
	s_waitcnt lgkmcnt(1)
	v_add_f32_e32 v1, v1, v21
	s_waitcnt lgkmcnt(0)
	v_add_f32_e32 v20, v20, v22
	ds_bpermute_b32 v21, v19, v1
	ds_bpermute_b32 v22, v19, v20
	s_and_saveexec_b64 s[18:19], s[38:39]
	s_cbranch_execz .LBB0_472
	s_waitcnt lgkmcnt(0)
	v_add_f32_e32 v22, v20, v22
	v_add_co_u32_e32 v20, vcc, 0x4000, v10
	v_add_f32_e32 v1, v1, v21
	s_nop 0
	v_addc_co_u32_e32 v21, vcc, 0, v11, vcc
	global_store_dword v[10:11], v1, off
	global_store_dword v[20:21], v22, off offset:1024
	s_branch .LBB0_472
